# P16 split into 4-round + rest with arrive-only barrier; WGs idle in round 6 start the final w2 GEMM early on even panel groups (tile index c^128)
# baseline (speedup 1.0000x reference)
.Lsp_reenter:
	s_cmpk_gt_i32 s2, 0x57f
	v_readfirstlane_b32 s5, v185
	s_cbranch_scc1 .LBB0_1982
	v_lshrrev_b32_e32 v0, 5, v185
	v_lshrrev_b32_e32 v2, 1, v185
	v_and_b32_e32 v0, 4, v0
	s_waitcnt lgkmcnt(0)
	v_bfe_u32 v1, v185, 2, 2
	v_and_b32_e32 v11, 24, v2
	v_or3_b32 v0, v0, v1, v11
	v_lshlrev_b32_e32 v1, 4, v185
	v_add_u32_e32 v8, 0x2000, v1
	v_lshrrev_b32_e32 v2, 7, v8
	s_movk_i32 s4, 0xe0
	v_and_b32_e32 v4, 32, v185
	v_and_or_b32 v3, v2, s4, v0
	v_bitop3_b32 v9, v1, v4, 48 bitop3:0x6c
	v_and_b32_e32 v10, 64, v185
	v_bfe_u32 v12, v185, 2, 4
	s_movk_i32 s4, 0xf0
	v_or_b32_e32 v1, v9, v10
	v_and_or_b32 v2, v2, s4, v12
	s_add_u32 s3, s76, 0x400000
	v_lshl_or_b32 v130, v2, 11, v1
	v_lshrrev_b32_e32 v2, 3, v185
	s_movk_i32 s4, 0x60
	s_addc_u32 s30, s77, 0
	v_and_or_b32 v0, v2, s4, v0
	s_movk_i32 s4, 0x70
	s_ashr_i32 s33, s2, 31
	v_lshl_or_b32 v132, v0, 11, v1
	v_and_or_b32 v0, v2, s4, v12
	s_lshr_b32 s4, s33, 29
	s_add_i32 s4, s2, s4
	s_lshr_b32 s10, s5, 6
	s_ashr_i32 s6, s4, 3
	s_and_b32 s4, s4, -8
	s_lshr_b32 s12, s5, 8
	s_lshl_b32 s31, s10, 10
	s_sub_i32 s4, s2, s4
	s_cmp_lt_i32 s4, 0
	s_movk_i32 s34, 0xb1
	s_cselect_b32 s7, s34, 0xb0
	s_mul_i32 s4, s4, s7
	s_add_i32 s4, s4, s6
	s_mul_hi_i32 s6, s4, 0x2e8ba2e9
	s_lshr_b32 s7, s6, 31
	s_ashr_i32 s6, s6, 4
	s_add_i32 s6, s6, s7
	s_lshl_b32 s7, s6, 2
	s_mulk_i32 s6, 0x58
	s_sub_i32 s6, s4, s6
	s_bfe_i32 s4, s6, 0x80000
	s_bfe_u32 s4, s4, 0x2000d
	s_add_i32 s8, s6, s4
	s_bfe_i32 s4, s8, 0x80000
	s_and_b32 s8, s8, 0xfc
	s_sub_i32 s6, s6, s8
	s_sext_i32_i16 s4, s4
	s_sext_i32_i8 s6, s6
	s_lshr_b32 s4, s4, 2
	s_add_i32 s22, s7, s6
	s_ashr_i32 s23, s22, 31
	s_bfe_i64 s[8:9], s[4:5], 0x100000
	s_lshl_b64 s[6:7], s[22:23], 19
	s_lshl_b64 s[8:9], s[8:9], 19
	s_add_u32 s26, s3, s8
	s_addc_u32 s27, s30, s9
	s_add_i32 s23, s31, 0
	s_add_i32 m0, s23, 0x10000
	v_lshl_or_b32 v128, v3, 11, v1
	global_load_lds_dwordx4 v132, s[26:27]
	s_add_i32 m0, s23, 0x12000
	s_add_u32 s8, s26, 0x40000
	global_load_lds_dwordx4 v128, s[26:27]
	s_addc_u32 s9, s27, 0
	s_add_i32 m0, s23, 0x14000
	v_lshl_or_b32 v134, v0, 11, v1
	global_load_lds_dwordx4 v132, s[8:9]
	s_add_i32 m0, s23, 0x16000
	s_add_u32 s24, s82, s6
	s_addc_u32 s25, s83, s7
	s_add_i32 s35, s23, 0x2000
	global_load_lds_dwordx4 v128, s[8:9]
	s_mov_b32 m0, s23
	s_add_u32 s6, s24, 0x40000
	global_load_lds_dwordx4 v134, s[24:25]
	s_mov_b32 m0, s35
	s_addc_u32 s7, s25, 0
	s_add_i32 s36, s23, 0x4000
	global_load_lds_dwordx4 v130, s[24:25]
	s_mov_b32 m0, s36
	s_add_i32 s37, s23, 0x6000
	global_load_lds_dwordx4 v134, s[6:7]
	s_mov_b32 m0, s37
	v_mov_b32_e32 v133, 0
	global_load_lds_dwordx4 v130, s[6:7]
	v_mov_b32_e32 v129, v133
	v_mov_b32_e32 v135, v133
	v_mov_b32_e32 v131, v133
	s_cmp_eq_u32 s12, 1
	s_mov_b32 s38, 0
	v_lshl_add_u64 v[6:7], s[26:27], 0, v[132:133]
	v_lshl_add_u64 v[4:5], s[26:27], 0, v[128:129]
	v_lshl_add_u64 v[0:1], s[24:25], 0, v[134:135]
	s_cselect_b64 s[6:7], -1, 0
	s_cmp_lg_u32 s12, 1
	v_lshl_add_u64 v[2:3], s[24:25], 0, v[130:131]
	s_cbranch_scc1 .LBB0_1969
	s_barrier
.LBB0_1969:
	s_add_u32 s8, s76, 0x60000
	s_addc_u32 s9, s77, 0
	s_lshl_b32 s10, s10, 5
	s_and_b32 s16, s10, 0x60
	s_mov_b64 s[10:11], 0x80
	s_add_i32 m0, s23, 0x18000
	v_lshl_add_u64 v[6:7], v[6:7], 0, s[10:11]
	s_lshl_b32 s13, s12, 13
	s_lshl_b32 s17, s16, 7
	s_waitcnt vmcnt(2)
	s_barrier
	global_load_lds_dwordx4 v[6:7], off
	v_lshl_add_u64 v[4:5], v[4:5], 0, s[10:11]
	s_add_i32 m0, s23, 0x1a000
	s_add_i32 s39, s23, 0x8000
	s_add_i32 s40, s23, 0xa000
	global_load_lds_dwordx4 v[4:5], off
	v_lshl_add_u64 v[0:1], v[0:1], 0, s[10:11]
	s_mov_b32 m0, s39
	s_add_u32 s14, s26, 0x40080
	global_load_lds_dwordx4 v[0:1], off
	v_lshl_add_u64 v[0:1], v[2:3], 0, s[10:11]
	s_mov_b32 m0, s40
	s_addc_u32 s15, s27, 0
	global_load_lds_dwordx4 v[0:1], off
	s_add_i32 m0, s23, 0x1c000
	v_lshl_add_u64 v[0:1], s[14:15], 0, v[132:133]
	global_load_lds_dwordx4 v[0:1], off
	v_lshl_add_u64 v[0:1], s[14:15], 0, v[128:129]
	s_add_i32 m0, s23, 0x1e000
	s_sext_i32_i8 s46, s4
	global_load_lds_dwordx4 v[0:1], off
	v_and_b32_e32 v0, 15, v185
	v_lshlrev_b32_e32 v1, 1, v11
	v_lshlrev_b32_e32 v2, 2, v185
	v_lshlrev_b32_e32 v3, 6, v185
	s_movk_i32 s4, 0x3c0
	v_lshl_or_b32 v149, s12, 6, v0
	v_lshl_or_b32 v0, v0, 6, v1
	v_and_b32_e32 v2, 32, v2
	v_and_or_b32 v1, v3, s4, v1
	v_bitop3_b32 v151, s17, v1, v2 bitop3:0xf6
	v_lshlrev_b32_e32 v1, 8, v185
	v_bitop3_b32 v0, v0, s13, v2 bitop3:0xde
	v_and_b32_e32 v1, 0x38000, v1
	v_lshlrev_b32_e32 v2, 11, v12
	v_or3_b32 v1, v9, v1, v2
	v_add_u32_e32 v136, v1, v10
	v_lshlrev_b32_e32 v1, 4, v8
	s_waitcnt vmcnt(6)
	s_cmpk_lt_u32 s5, 0x100
	v_and_b32_e32 v1, 0x78000, v1
	s_cselect_b64 s[12:13], -1, 0
	v_or3_b32 v1, v9, v1, v2
	s_add_i32 s43, 0, 0x10000
	s_add_i32 s44, 0, 0x14000
	s_ashr_i32 s41, s64, 31
	s_mov_b32 s42, s64
	v_or_b32_e32 v153, s16, v11
	v_mov_b32_e32 v137, v133
	v_add_u32_e32 v138, v1, v10
	v_mov_b32_e32 v139, v133
	v_mov_b32_e32 v141, 0
	v_mov_b32_e32 v143, 0
	v_add_u32_e32 v155, s43, v151
	v_add_u32_e32 v157, s44, v151
	v_add_u32_e32 v158, 0, v0
	v_mov_b32_e32 v159, 0x358637bd
	s_movk_i32 s45, 0x1600
	s_cmpk_ge_u32 s2, 0x400
	s_movk_i32 s51, 0x400
	s_cselect_b32 s51, 0x580, s51
	v_mov_b32_e32 v140, s51
	s_add_i32 s51, s51, -1
	v_mov_b32_e32 v142, s51
	s_barrier
	s_branch .LBB0_1972

.LBB0_1981:
	s_waitcnt vmcnt(0)
	s_barrier
	s_cmpk_ge_u32 s2, 0x400
	s_cbranch_scc1 .Lsp_afterB
	s_waitcnt vmcnt(0) lgkmcnt(0)
	v_readlane_b32 s21, v242, 63
	s_add_u32 s21, s21, 1
	v_writelane_b32 v242, s21, 63
	v_readlane_b32 s12, v242, 1
	v_readlane_b32 s13, v242, 2
	s_mov_b64 s[14:15], exec
	s_and_b64 s[12:13], s[14:15], s[12:13]
	s_mov_b64 exec, s[12:13]
	s_cbranch_execz .Lsp_arr_done
	v_mov_b32_e32 v0, 0x21020
	ds_read2_b32 v[2:3], v0 offset1:1
	s_lshl_b32 s16, s84, 8
	s_add_u32 s16, s76, s16
	s_addc_u32 s17, s77, 0
	v_mov_b32_e32 v1, 0x1000
	v_mov_b32_e32 v4, 1
	global_atomic_add v5, v1, v4, s[16:17] offset:1024 sc0
	s_waitcnt vmcnt(0) lgkmcnt(0)
	v_readfirstlane_b32 s18, v5
	v_readfirstlane_b32 s19, v2
	s_mul_i32 s22, s19, s21
	s_add_u32 s18, s18, 1
	s_cmp_lg_u32 s18, s22
	s_cbranch_scc1 .Lsp_arr_done
	buffer_wbl2 sc1
	s_waitcnt vmcnt(0)
	v_mov_b32_e32 v1, 0x3000
	global_atomic_add v1, v4, s[76:77] offset:1024
.Lsp_arr_done:
	s_mov_b64 exec, s[14:15]
	s_add_u32 s2, s2, 0x400
	s_branch .Lsp_reenter
.Lsp_afterB:
	s_sub_u32 s2, s2, 0x400
.LBB0_1982:
	s_cmp_gt_i32 s79, 17
	s_cselect_b64 s[4:5], -1, 0
	s_and_b64 s[0:1], s[0:1], s[4:5]
	s_andn2_b64 vcc, exec, s[0:1]
	s_cbranch_vccnz .LBB0_2036
	s_waitcnt vmcnt(0) lgkmcnt(0)
	s_barrier
	v_readlane_b32 s21, v242, 63
	s_add_u32 s21, s21, 1
	v_readlane_b32 s12, v242, 1
	v_readlane_b32 s13, v242, 2
	s_mov_b64 s[14:15], exec
	s_and_b64 s[12:13], s[14:15], s[12:13]
	s_mov_b64 exec, s[12:13]
	s_cbranch_execz .Lxb_done_14
	v_mov_b32_e32 v0, 0x21020
	ds_read2_b32 v[2:3], v0 offset1:1
	s_lshl_b32 s16, s84, 8
	s_add_u32 s16, s76, s16
	s_addc_u32 s17, s77, 0
	v_mov_b32_e32 v1, 0x1000
	v_mov_b32_e32 v4, 1
	global_atomic_add v5, v1, v4, s[16:17] offset:1024 sc0
	buffer_inv sc1
	s_waitcnt vmcnt(0) lgkmcnt(0)
	v_readfirstlane_b32 s18, v5
	v_readfirstlane_b32 s19, v2
	v_readfirstlane_b32 s20, v3
	v_mov_b32_e32 v1, 0x3000
	s_mul_i32 s22, s19, s21
	s_mul_i32 s23, s20, s21
	s_add_u32 s18, s18, 1
	s_cmpk_lt_u32 s2, 0x80
	s_cbranch_scc1 .Lsp_busy
	s_sub_u32 s23, s23, s20
.Lsp_busy:
	s_cmp_lg_u32 s18, s22
	s_cbranch_scc1 .Lxb_spin_14
	buffer_wbl2 sc1
	s_waitcnt vmcnt(0)
	global_atomic_add v1, v4, s[76:77] offset:1024

.LBB0_2036:
	s_cmp_lt_i32 s78, 18
	s_cselect_b64 s[6:7], -1, 0
	s_and_b64 s[0:1], s[6:7], s[4:5]
	s_andn2_b64 vcc, exec, s[0:1]
	s_cbranch_vccnz .LBB0_2065
	s_cmpk_gt_i32 s2, 0xff
	v_readfirstlane_b32 s4, v185
	s_cbranch_scc1 .LBB0_2065
	s_xor_b32 s2, s2, 0x80
	s_ashr_i32 s3, s2, 31
	s_lshr_b32 s0, s3, 29
	s_add_i32 s9, s2, s0
	s_and_b32 s0, s9, -8
	s_sub_i32 s5, s2, s0
	s_cmp_gt_i32 s5, -1
	s_cbranch_scc0 .LBB0_2040
	s_lshl_b32 s8, s5, 5
	s_ashr_i32 s1, s9, 3
	s_cbranch_execz .LBB0_2041
	s_branch .LBB0_2042
